# P4 queue reorder + attention bias-table fill with 5 loads in flight
# speedup vs baseline: 1.0141x; 1.0003x over previous
.LBB0_877:
	s_mov_b64 s[4:5], 0
	s_and_b64 vcc, exec, s[2:3]
	s_mov_b64 s[36:37], 0
	s_cbranch_vccz .LBB0_1032
	v_mov_b32_e32 v0, v252
	s_waitcnt vmcnt(63) expcnt(7) lgkmcnt(15)
	v_readfirstlane_b32 s6, v0
	s_barrier
	s_load_dwordx2 s[2:3], s[0:1], 0x40
	s_ashr_i32 s33, s6, 6
	s_mul_i32 s8, s33, 0x101
	v_and_b32_e32 v168, 63, v0
	s_mul_i32 s7, s33, 0x410
	s_ashr_i32 s9, s8, 31
	v_mov_b32_e32 v169, v1
	s_add_i32 s30, s7, 0
	v_lshl_add_u64 v[2:3], s[8:9], 0, v[168:169]
	v_or_b32_e32 v4, 0xffffffc0, v168
	v_lshl_add_u32 v5, v168, 2, s30
	s_waitcnt lgkmcnt(0)
	v_lshl_add_u64 v[2:3], v[2:3], 2, s[2:3]
	s_mov_b64 s[2:3], 0
	global_load_dword v243, v[2:3], off
	global_load_dword v248, v[2:3], off offset:256
	global_load_dword v249, v[2:3], off offset:512
	global_load_dword v250, v[2:3], off offset:768
	v_cmp_eq_u32_e32 vcc, 0xffffffc0, v4
	s_and_saveexec_b64 s[2:3], vcc
	global_load_dword v251, v[2:3], off offset:1024
	s_waitcnt vmcnt(0)
	v_mul_f32_e32 v251, 0x3fb8aa3b, v251
	ds_write_b32 v5, v251 offset:1024
	s_or_b64 exec, exec, s[2:3]
	v_mul_f32_e32 v243, 0x3fb8aa3b, v243
	v_mul_f32_e32 v248, 0x3fb8aa3b, v248
	v_mul_f32_e32 v249, 0x3fb8aa3b, v249
	v_mul_f32_e32 v250, 0x3fb8aa3b, v250
	ds_write_b32 v5, v243
	ds_write_b32 v5, v248 offset:256
	ds_write_b32 v5, v249 offset:512
	ds_write_b32 v5, v250 offset:768
	s_add_i32 s2, s18, 0xfffffba9
	s_lshl_b32 s3, s2, 5
	s_mul_hi_u32 s38, s2, 0x88000
	s_mul_i32 s39, s2, 0x88000
	s_andn2_b32 s6, s6, 63
	s_lshl_b32 s2, s2, 3
	s_ashr_i32 s7, s6, 31
	s_add_i32 s2, s33, s2
	s_add_i32 s76, s3, 0x8000
	s_mul_hi_i32 s40, s2, 0x11000
	s_mul_i32 s41, s2, 0x11000
	s_add_u32 s8, s79, s39
	v_readlane_b32 s2, v254, 46
	s_addc_u32 s9, s2, s38
	s_lshl_b64 s[2:3], s[6:7], 1
	s_add_u32 s10, s8, s2
	s_addc_u32 s11, s9, s3
	v_readlane_b32 s8, v254, 48
	s_add_u32 s8, s8, s41
	v_readlane_b32 s9, v254, 50
	s_addc_u32 s9, s9, s40
	v_and_b32_e32 v169, 31, v0
	v_lshrrev_b32_e32 v15, 5, v168
	s_add_u32 s36, s95, s2
	s_addc_u32 s37, s22, s3
	v_lshlrev_b32_e32 v0, 4, v15
	v_or_b32_e32 v166, s76, v169
	v_mov_b32_e32 v167, v1
	v_lshl_add_u64 v[2:3], s[36:37], 0, v[0:1]
	v_lshlrev_b64 v[4:5], 10, v[166:167]
	s_lshl_b64 s[36:37], s[76:77], 10
	v_lshl_add_u64 v[4:5], v[2:3], 0, v[4:5]
	v_lshl_add_u64 v[2:3], v[2:3], 0, s[36:37]
	s_movk_i32 s31, 0x7000
	v_add_co_u32_e32 v2, vcc, s31, v2
	s_waitcnt lgkmcnt(0)
	s_nop 0
	v_addc_co_u32_e32 v3, vcc, 0, v3, vcc
	s_barrier
	global_load_dwordx4 v[16:19], v[4:5], off
	global_load_dwordx4 v[20:23], v[4:5], off offset:32
	global_load_dwordx4 v[24:27], v[4:5], off offset:64
	global_load_dwordx4 v[28:31], v[4:5], off offset:96
	global_load_dwordx4 v[32:35], v[2:3], off offset:3072
	global_load_dwordx4 v[36:39], v[2:3], off offset:3104
	global_load_dwordx4 v[40:43], v[2:3], off offset:3136
	global_load_dwordx4 v[44:47], v[2:3], off offset:3168
	s_mul_i32 s36, s33, 0x1bf0
	v_lshlrev_b32_e32 v48, 4, v168
	v_lshlrev_b32_e32 v49, 4, v169
	v_lshl_add_u64 v[172:173], s[10:11], 0, v[0:1]
	s_add_i32 s10, s30, s36
	v_add_u32_e32 v189, s10, v48
	v_lshl_or_b32 v0, v15, 10, v49
	s_add_u32 s10, s39, 0xa5ee240
	v_lshl_add_u64 v[174:175], s[8:9], 0, v[0:1]
	v_or_b32_e32 v170, s41, v0
	s_addc_u32 s11, s38, 0
	v_lshlrev_b32_e32 v0, 10, v169
	v_lshrrev_b32_e32 v50, 1, v168
	v_lshl_add_u64 v[48:49], s[10:11], 0, v[0:1]
	v_mov_b32_e32 v14, v1
	v_lshlrev_b32_e32 v165, 2, v15
	v_and_or_b32 v48, v50, 16, v48
	v_mov_b32_e32 v15, v1
	v_mov_b32_e32 v2, v1
	v_mov_b32_e32 v3, v1
	v_mov_b32_e32 v4, v1
	v_mov_b32_e32 v5, v1
	v_mov_b32_e32 v6, v1
	v_mov_b32_e32 v7, v1
	v_mov_b32_e32 v8, v1
	v_mov_b32_e32 v9, v1
	v_mov_b32_e32 v10, v1
	v_mov_b32_e32 v11, v1
	v_mov_b32_e32 v12, v1
	v_mov_b32_e32 v13, v1
	v_mov_b32_e32 v0, v1
	v_lshl_add_u64 v[176:177], v[48:49], 0, s[2:3]
	v_mov_b64_e32 v[62:63], v[14:15]
	v_mov_b64_e32 v[78:79], v[14:15]
	s_mov_b32 s31, 3
	s_mov_b32 s33, 0
	v_sub_u32_e32 v188, v169, v165
	v_mov_b32_e32 v171, s40
	v_mov_b32_e32 v190, 0
	v_mov_b32_e32 v191, 0xf149f2ca
	s_mov_b32 s10, 0
	v_mov_b64_e32 v[60:61], v[12:13]
	v_mov_b64_e32 v[58:59], v[10:11]
	v_mov_b64_e32 v[56:57], v[8:9]
	v_mov_b64_e32 v[54:55], v[6:7]
	v_mov_b64_e32 v[52:53], v[4:5]
	v_mov_b64_e32 v[50:51], v[2:3]
	s_waitcnt vmcnt(7)
	s_waitcnt vmcnt(6)
	s_waitcnt vmcnt(5)
	s_waitcnt vmcnt(4)
	s_waitcnt vmcnt(3)
	s_waitcnt vmcnt(2)
	s_waitcnt vmcnt(1)
	s_waitcnt vmcnt(0)
	ds_write_b128 v189, v[16:19] offset:16384
	ds_write_b128 v189, v[20:23] offset:17408
	ds_write_b128 v189, v[24:27] offset:18432
	ds_write_b128 v189, v[28:31] offset:19456
	ds_write_b128 v189, v[32:35] offset:20480
	ds_write_b128 v189, v[36:39] offset:21504
	ds_write_b128 v189, v[40:43] offset:22528
	ds_write_b128 v189, v[44:47] offset:23552
	v_mov_b64_e32 v[30:31], v[14:15]
	v_mov_b64_e32 v[46:47], v[14:15]
	v_mov_b64_e32 v[28:29], v[12:13]
	v_mov_b64_e32 v[26:27], v[10:11]
	v_mov_b64_e32 v[24:25], v[8:9]
	v_mov_b64_e32 v[22:23], v[6:7]
	v_mov_b64_e32 v[20:21], v[4:5]
	v_mov_b64_e32 v[18:19], v[2:3]
	v_mov_b64_e32 v[16:17], v[0:1]
	v_mov_b64_e32 v[48:49], v[0:1]
	v_mov_b64_e32 v[44:45], v[12:13]
	v_mov_b64_e32 v[42:43], v[10:11]
	v_mov_b64_e32 v[40:41], v[8:9]
	v_mov_b64_e32 v[38:39], v[6:7]
	v_mov_b64_e32 v[36:37], v[4:5]
	v_mov_b64_e32 v[34:35], v[2:3]
	v_mov_b64_e32 v[32:33], v[0:1]
	v_mov_b64_e32 v[76:77], v[12:13]
	v_mov_b64_e32 v[74:75], v[10:11]
	v_mov_b64_e32 v[72:73], v[8:9]
	v_mov_b64_e32 v[70:71], v[6:7]
	v_mov_b64_e32 v[68:69], v[4:5]
	v_mov_b64_e32 v[66:67], v[2:3]
	v_mov_b64_e32 v[64:65], v[0:1]
	v_mov_b32_e32 v209, 0xf149f2ca
	v_mov_b32_e32 v15, 0
	s_mov_b32 s11, 0

.LBB0_1129:
	v_mov_b32_e32 v0, v252
	s_waitcnt vmcnt(63) expcnt(7) lgkmcnt(15)
	v_readfirstlane_b32 s4, v0
	s_barrier
	s_load_dwordx2 s[2:3], s[0:1], 0x40
	s_ashr_i32 s8, s4, 6
	s_mul_i32 s6, s8, 0x101
	v_and_b32_e32 v168, 63, v0
	s_mul_i32 s5, s8, 0x410
	s_ashr_i32 s7, s6, 31
	v_mov_b32_e32 v169, v1
	s_add_i32 s10, s5, 0
	v_lshl_add_u64 v[2:3], s[6:7], 0, v[168:169]
	v_or_b32_e32 v4, 0xffffffc0, v168
	v_lshl_add_u32 v5, v168, 2, s10
	s_waitcnt lgkmcnt(0)
	v_lshl_add_u64 v[2:3], v[2:3], 2, s[2:3]
	s_mov_b64 s[2:3], 0
	global_load_dword v243, v[2:3], off
	global_load_dword v248, v[2:3], off offset:256
	global_load_dword v249, v[2:3], off offset:512
	global_load_dword v250, v[2:3], off offset:768
	v_cmp_eq_u32_e32 vcc, 0xffffffc0, v4
	s_and_saveexec_b64 s[2:3], vcc
	global_load_dword v251, v[2:3], off offset:1024
	s_waitcnt vmcnt(0)
	v_mul_f32_e32 v251, 0x3fb8aa3b, v251
	ds_write_b32 v5, v251 offset:1024
	s_or_b64 exec, exec, s[2:3]
	v_mul_f32_e32 v243, 0x3fb8aa3b, v243
	v_mul_f32_e32 v248, 0x3fb8aa3b, v248
	v_mul_f32_e32 v249, 0x3fb8aa3b, v249
	v_mul_f32_e32 v250, 0x3fb8aa3b, v250
	ds_write_b32 v5, v243
	ds_write_b32 v5, v248 offset:256
	ds_write_b32 v5, v249 offset:512
	ds_write_b32 v5, v250 offset:768
	s_add_i32 s2, s18, 0xfffffbd9
	s_lshl_b32 s3, s2, 7
	s_and_b32 s9, s3, 0x180
	s_or_b32 s3, s9, 7
	s_lshr_b32 s11, s2, 2
	s_sub_i32 s33, s3, s11
	s_and_b32 s2, s33, 0x7f
	s_lshl_b32 s2, s2, 16
	v_readlane_b32 s3, v254, 34
	s_add_u32 s2, s3, s2
	v_readlane_b32 s3, v254, 40
	s_addc_u32 s3, s3, 0
	s_andn2_b32 s4, s4, 63
	s_lshl_b32 s6, s33, 16
	s_ashr_i32 s5, s4, 31
	s_and_b32 s6, s6, 0x1800000
	s_add_u32 s6, s2, s6
	s_addc_u32 s7, s3, 0
	s_lshl_b64 s[2:3], s[4:5], 1
	s_add_u32 s6, s6, s2
	s_addc_u32 s7, s7, s3
	v_and_b32_e32 v169, 31, v0
	v_lshrrev_b32_e32 v36, 5, v168
	s_add_u32 s30, s95, s2
	s_addc_u32 s31, s22, s3
	v_lshlrev_b32_e32 v0, 4, v36
	v_lshl_or_b32 v166, s33, 6, v169
	v_lshl_add_u64 v[2:3], s[30:31], 0, v[0:1]
	v_lshlrev_b32_e32 v4, 10, v166
	v_mov_b32_e32 v5, v1
	v_or_b32_e32 v165, 32, v166
	v_lshl_add_u64 v[16:17], v[2:3], 0, v[4:5]
	v_lshlrev_b32_e32 v4, 10, v165
	s_waitcnt lgkmcnt(0)
	s_barrier
	v_lshl_add_u64 v[2:3], v[2:3], 0, v[4:5]
	global_load_dwordx4 v[4:7], v[16:17], off
	global_load_dwordx4 v[8:11], v[16:17], off offset:32
	global_load_dwordx4 v[12:15], v[16:17], off offset:64
	s_nop 0
	global_load_dwordx4 v[16:19], v[16:17], off offset:96
	s_nop 0
	global_load_dwordx4 v[20:23], v[2:3], off
	global_load_dwordx4 v[24:27], v[2:3], off offset:32
	global_load_dwordx4 v[28:31], v[2:3], off offset:64
	global_load_dwordx4 v[32:35], v[2:3], off offset:96
	v_lshlrev_b32_e32 v37, 4, v169
	v_lshlrev_b32_e32 v167, 2, v36
	v_lshl_or_b32 v39, v36, 10, v37
	v_lshl_add_u64 v[36:37], s[6:7], 0, v[0:1]
	s_mov_b32 s6, 0xfff80000
	s_mov_b32 s7, -1
	v_lshl_add_u64 v[172:173], v[36:37], 0, s[6:7]
	s_sub_i32 s6, 7, s11
	s_sub_i32 s7, s9, s11
	s_and_b32 s6, s6, 0x7f
	s_add_i32 s7, s7, 7
	s_min_u32 s9, s6, 8
	s_lshr_b32 s7, s7, 4
	s_lshl_b32 s31, s6, 13
	s_sub_i32 s11, 7, s9
	s_lshl_b32 s33, s9, 6
	s_lshl_b32 s9, s9, 13
	s_and_b32 s6, s7, 0xffffff8
	s_mul_i32 s30, s8, 0x1bf0
	s_sub_i32 s7, 0, s9
	s_add_i32 s6, s8, s6
	v_lshlrev_b32_e32 v38, 4, v168
	s_add_i32 s30, s10, s30
	s_ashr_i32 s8, s7, 31
	v_or_b32_e32 v174, s7, v39
	s_ashr_i32 s7, s6, 31
	v_add_u32_e32 v188, s30, v38
	s_lshl_b64 s[6:7], s[6:7], 20
	s_sub_i32 s30, 0, s33
	v_subrev_u32_e32 v36, s9, v39
	s_or_b32 s6, s6, s31
	v_mov_b32_e32 v2, v1
	v_mov_b32_e32 v3, v1
	v_mov_b32_e32 v0, v1
	v_add_u32_e32 v170, 0x10000, v36
	s_add_u32 s6, s86, s6
	v_mov_b32_e32 v171, v1
	v_sub_u32_e32 v189, s33, v167
	v_or_b32_e32 v176, 0x200, v174
	v_mov_b32_e32 v177, s8
	v_mov_b32_e32 v175, s8
	s_addc_u32 s7, s87, s7
	v_mov_b32_e32 v190, 0
	v_mov_b32_e32 v191, 0xf149f2ca
	v_mov_b32_e32 v208, 0xf149f2ca
	s_waitcnt vmcnt(7)
	s_waitcnt vmcnt(6)
	s_waitcnt vmcnt(5)
	s_waitcnt vmcnt(4)
	s_waitcnt vmcnt(3)
	s_waitcnt vmcnt(2)
	s_waitcnt vmcnt(1)
	s_waitcnt vmcnt(0)
	ds_write_b128 v188, v[4:7] offset:16384
	ds_write_b128 v188, v[8:11] offset:17408
	ds_write_b128 v188, v[12:15] offset:18432
	ds_write_b128 v188, v[16:19] offset:19456
	ds_write_b128 v188, v[20:23] offset:20480
	ds_write_b128 v188, v[24:27] offset:21504
	ds_write_b128 v188, v[28:31] offset:22528
	ds_write_b128 v188, v[32:35] offset:23552
	v_mov_b32_e32 v14, v1
	v_mov_b32_e32 v15, v1
	v_mov_b32_e32 v4, v1
	v_mov_b32_e32 v5, v1
	v_mov_b32_e32 v6, v1
	v_mov_b32_e32 v7, v1
	v_mov_b32_e32 v8, v1
	v_mov_b32_e32 v9, v1
	v_mov_b32_e32 v10, v1
	v_mov_b32_e32 v11, v1
	v_mov_b32_e32 v12, v1
	v_mov_b32_e32 v13, v1
	v_mov_b64_e32 v[30:31], v[14:15]
	v_mov_b64_e32 v[62:63], v[14:15]
	v_mov_b64_e32 v[46:47], v[14:15]
	v_mov_b64_e32 v[78:79], v[14:15]
	v_mov_b64_e32 v[28:29], v[12:13]
	v_mov_b64_e32 v[26:27], v[10:11]
	v_mov_b64_e32 v[24:25], v[8:9]
	v_mov_b64_e32 v[22:23], v[6:7]
	v_mov_b64_e32 v[20:21], v[4:5]
	v_mov_b64_e32 v[18:19], v[2:3]
	v_mov_b64_e32 v[16:17], v[0:1]
	v_mov_b64_e32 v[60:61], v[12:13]
	v_mov_b64_e32 v[58:59], v[10:11]
	v_mov_b64_e32 v[56:57], v[8:9]
	v_mov_b64_e32 v[54:55], v[6:7]
	v_mov_b64_e32 v[52:53], v[4:5]
	v_mov_b64_e32 v[50:51], v[2:3]
	v_mov_b64_e32 v[48:49], v[0:1]
	v_mov_b64_e32 v[44:45], v[12:13]
	v_mov_b64_e32 v[42:43], v[10:11]
	v_mov_b64_e32 v[40:41], v[8:9]
	v_mov_b64_e32 v[38:39], v[6:7]
	v_mov_b64_e32 v[36:37], v[4:5]
	v_mov_b64_e32 v[34:35], v[2:3]
	v_mov_b64_e32 v[32:33], v[0:1]
	v_mov_b64_e32 v[76:77], v[12:13]
	v_mov_b64_e32 v[74:75], v[10:11]
	v_mov_b64_e32 v[72:73], v[8:9]
	v_mov_b64_e32 v[70:71], v[6:7]
	v_mov_b64_e32 v[68:69], v[4:5]
	v_mov_b64_e32 v[66:67], v[2:3]
	v_mov_b64_e32 v[64:65], v[0:1]
	v_mov_b32_e32 v15, 0

.LBB0_1429:
	v_mov_b32_e32 v4, v252
	s_waitcnt vmcnt(63) expcnt(7) lgkmcnt(15)
	v_readfirstlane_b32 s4, v4
	s_barrier
	s_load_dwordx2 s[2:3], s[0:1], 0x40
	s_ashr_i32 s10, s4, 6
	v_and_b32_e32 v173, 63, v4
	s_mul_i32 s6, s10, 0x101
	s_mul_i32 s5, s10, 0x410
	v_add_u32_e32 v2, s6, v173
	s_add_i32 s8, s5, 0
	v_ashrrev_i32_e32 v3, 31, v2
	v_or_b32_e32 v0, 0xffffffc0, v173
	v_lshl_add_u32 v5, v173, 2, s8
	s_waitcnt lgkmcnt(0)
	v_lshl_add_u64 v[2:3], v[2:3], 2, s[2:3]
	s_mov_b64 s[2:3], 0
	global_load_dword v243, v[2:3], off
	global_load_dword v248, v[2:3], off offset:256
	global_load_dword v249, v[2:3], off offset:512
	global_load_dword v250, v[2:3], off offset:768
	v_cmp_eq_u32_e32 vcc, 0xffffffc0, v0
	s_and_saveexec_b64 s[2:3], vcc
	global_load_dword v251, v[2:3], off offset:1024
	s_waitcnt vmcnt(0)
	v_mul_f32_e32 v251, 0x3fb8aa3b, v251
	ds_write_b32 v5, v251 offset:1024
	s_or_b64 exec, exec, s[2:3]
	v_mul_f32_e32 v243, 0x3fb8aa3b, v243
	v_mul_f32_e32 v248, 0x3fb8aa3b, v248
	v_mul_f32_e32 v249, 0x3fb8aa3b, v249
	v_mul_f32_e32 v250, 0x3fb8aa3b, v250
	ds_write_b32 v5, v243
	ds_write_b32 v5, v248 offset:256
	ds_write_b32 v5, v249 offset:512
	ds_write_b32 v5, v250 offset:768
	s_add_i32 s11, s18, 0xffb9
	s_and_b32 s9, s11, 0xffff
	s_mul_i32 s2, s9, 0x8889
	s_lshr_b32 s2, s2, 22
	s_lshl_b32 s3, s2, 7
	s_mulk_i32 s2, 0x78
	s_sub_i32 s2, s11, s2
	s_add_i32 s2, s2, 8
	s_and_b32 s2, s2, 0xffff
	s_add_i32 s33, s3, s2
	s_lshr_b32 s2, s33, 7
	s_lshl_b32 s76, s2, 22
	s_lshl_b32 s2, s2, 3
	s_and_b32 s6, s4, 0xffffffc0
	s_add_i32 s2, s10, s2
	s_ashr_i32 s7, s6, 31
	s_ashr_i32 s3, s2, 31
	s_lshl_b64 s[2:3], s[2:3], 20
	s_lshl_b64 s[4:5], s[6:7], 1
	v_lshrrev_b32_e32 v5, 5, v173
	s_add_u32 s30, s95, s4
	v_and_b32_e32 v172, 31, v4
	s_addc_u32 s31, s22, s5
	v_lshlrev_b32_e32 v0, 4, v5
	v_lshl_add_u64 v[2:3], s[30:31], 0, v[0:1]
	v_lshl_or_b32 v0, s33, 6, v172
	v_lshlrev_b64 v[6:7], 10, v[0:1]
	v_or_b32_e32 v162, 32, v0
	v_mov_b32_e32 v163, v1
	v_lshl_add_u64 v[18:19], v[2:3], 0, v[6:7]
	v_lshlrev_b64 v[6:7], 10, v[162:163]
	s_waitcnt lgkmcnt(0)
	s_barrier
	v_lshl_add_u64 v[2:3], v[2:3], 0, v[6:7]
	global_load_dwordx4 v[6:9], v[18:19], off
	global_load_dwordx4 v[10:13], v[18:19], off offset:32
	global_load_dwordx4 v[14:17], v[18:19], off offset:64
	s_nop 0
	global_load_dwordx4 v[18:21], v[18:19], off offset:96
	s_nop 0
	global_load_dwordx4 v[22:25], v[2:3], off
	global_load_dwordx4 v[26:29], v[2:3], off offset:32
	global_load_dwordx4 v[30:33], v[2:3], off offset:64
	global_load_dwordx4 v[34:37], v[2:3], off offset:96
	s_mulk_i32 s10, 0x1bf0
	v_lshlrev_b32_e32 v38, 4, v173
	s_add_i32 s10, s8, s10
	v_and_b32_e32 v3, 32, v4
	v_add_u32_e32 v174, s10, v38
	s_lshl_b32 s10, s11, 16
	v_lshlrev_b32_e32 v2, 10, v172
	v_lshrrev_b32_e32 v3, 1, v3
	v_or3_b32 v2, s10, v2, v3
	s_lshl_b64 s[10:11], s[76:77], 1
	s_add_u32 s10, s10, s4
	v_mov_b32_e32 v3, v1
	s_addc_u32 s11, s11, s5
	v_lshl_add_u64 v[2:3], s[10:11], 0, v[2:3]
	s_mul_hi_u32 s10, s9, 0x2222223
	s_mul_hi_u32 s11, s10, 0x780000
	s_mul_i32 s30, s10, 0x780000
	v_subrev_co_u32_e32 v166, vcc, s30, v2
	v_mov_b32_e32 v2, s11
	s_lshl_b32 s9, s9, 13
	v_subb_co_u32_e32 v167, vcc, v3, v2, vcc
	s_add_u32 s2, s2, s9
	v_lshlrev_b32_e32 v2, 4, v172
	v_lshlrev_b32_e32 v3, 10, v5
	v_or3_b32 v2, v3, v2, s2
	s_addc_u32 s3, s3, 0
	v_or_b32_e32 v3, 0x200, v2
	s_mul_i32 s10, s10, 0xf0000
	v_mov_b32_e32 v4, s3
	v_subrev_co_u32_e32 v168, vcc, s10, v3
	v_lshlrev_b32_e32 v165, 2, v5
	s_nop 0
	v_subbrev_co_u32_e32 v169, vcc, 0, v4, vcc
	v_subrev_co_u32_e32 v170, vcc, s10, v2
	v_sub_u32_e32 v2, v172, v165
	s_nop 0
	v_subbrev_co_u32_e32 v171, vcc, 0, v4, vcc
	v_add_u32_e32 v177, 0x220, v2
	v_mov_b32_e32 v2, v1
	v_mov_b32_e32 v3, v1
	v_mov_b32_e32 v4, v1
	v_mov_b32_e32 v5, v1
	v_mov_b32_e32 v175, 0
	v_mov_b32_e32 v189, 0xf149f2ca
	s_mov_b32 s9, -1
	v_mov_b32_e32 v199, 0xf149f2ca
	v_mov_b32_e32 v176, 0
	s_waitcnt vmcnt(7)
	s_waitcnt vmcnt(6)
	s_waitcnt vmcnt(5)
	s_waitcnt vmcnt(4)
	s_waitcnt vmcnt(3)
	s_waitcnt vmcnt(2)
	s_waitcnt vmcnt(1)
	s_waitcnt vmcnt(0)
	ds_write_b128 v174, v[6:9] offset:16384
	ds_write_b128 v174, v[10:13] offset:17408
	ds_write_b128 v174, v[14:17] offset:18432
	ds_write_b128 v174, v[18:21] offset:19456
	ds_write_b128 v174, v[22:25] offset:20480
	ds_write_b128 v174, v[26:29] offset:21504
	ds_write_b128 v174, v[30:33] offset:22528
	ds_write_b128 v174, v[34:37] offset:23552
	v_mov_b32_e32 v16, v1
	v_mov_b32_e32 v17, v1
	v_mov_b32_e32 v6, v1
	v_mov_b32_e32 v7, v1
	v_mov_b32_e32 v8, v1
	v_mov_b32_e32 v9, v1
	v_mov_b32_e32 v10, v1
	v_mov_b32_e32 v11, v1
	v_mov_b32_e32 v12, v1
	v_mov_b32_e32 v13, v1
	v_mov_b32_e32 v14, v1
	v_mov_b32_e32 v15, v1
	v_mov_b64_e32 v[48:49], v[16:17]
	v_mov_b64_e32 v[32:33], v[16:17]
	v_mov_b64_e32 v[64:65], v[16:17]
	v_mov_b64_e32 v[46:47], v[14:15]
	v_mov_b64_e32 v[44:45], v[12:13]
	v_mov_b64_e32 v[42:43], v[10:11]
	v_mov_b64_e32 v[40:41], v[8:9]
	v_mov_b64_e32 v[38:39], v[6:7]
	v_mov_b64_e32 v[36:37], v[4:5]
	v_mov_b64_e32 v[34:35], v[2:3]
	v_mov_b64_e32 v[30:31], v[14:15]
	v_mov_b64_e32 v[28:29], v[12:13]
	v_mov_b64_e32 v[26:27], v[10:11]
	v_mov_b64_e32 v[24:25], v[8:9]
	v_mov_b64_e32 v[22:23], v[6:7]
	v_mov_b64_e32 v[20:21], v[4:5]
	v_mov_b64_e32 v[18:19], v[2:3]
	v_mov_b64_e32 v[62:63], v[14:15]
	v_mov_b64_e32 v[60:61], v[12:13]
	v_mov_b64_e32 v[58:59], v[10:11]
	v_mov_b64_e32 v[56:57], v[8:9]
	v_mov_b64_e32 v[54:55], v[6:7]
	v_mov_b64_e32 v[52:53], v[4:5]
	v_mov_b64_e32 v[50:51], v[2:3]
